# P0 mods GEMV loop software-pipelined (double-buffered 8-row load sets, counted vmcnt) on top of P0 rebalance/unroll and P3 epilogue
# speedup vs baseline: 1.0023x; 1.0023x over previous
; __device__ __forceinline__ void mods_item(CArgs a, float* mods, LAS float* scr, int item, int lane) {
;     ...
;     const float* wp = a->w_ada + (size_t)k0 * (NMOD * D) + col;
; #pragma unroll 8
;     for (int kk = 0; kk < 128; ++kk) {
;         const f32x4 w = __builtin_nontemporal_load((const f32x4*)(wp + (size_t)kk * (NMOD * D)));
;         s0 += w * scr[kk]; s1 += w * scr[128 + kk]; s2 += w * scr[256 + kk]; s3 += w * scr[384 + kk];
;     }
.LBB0_24:
	v_lshl_add_u64 v[136:137], v[18:19], 0, s[16:17]
	v_add_co_u32_e32 v138, vcc, s18, v136
	s_nop 1
	v_addc_co_u32_e32 v139, vcc, 0, v137, vcc
	v_add_co_u32_e32 v140, vcc, s19, v136
	s_nop 1
	v_addc_co_u32_e32 v141, vcc, 0, v137, vcc
	v_add_co_u32_e32 v142, vcc, s20, v136
	s_nop 1
	v_addc_co_u32_e32 v143, vcc, 0, v137, vcc
	v_add_co_u32_e32 v144, vcc, s21, v136
	s_nop 1
	v_addc_co_u32_e32 v145, vcc, 0, v137, vcc
	v_add_co_u32_e32 v146, vcc, s22, v136
	s_nop 1
	v_addc_co_u32_e32 v147, vcc, 0, v137, vcc
	v_add_co_u32_e32 v148, vcc, s23, v136
	s_nop 1
	v_addc_co_u32_e32 v149, vcc, 0, v137, vcc
	v_add_co_u32_e32 v150, vcc, s24, v136
	s_nop 1
	v_addc_co_u32_e32 v151, vcc, 0, v137, vcc
	global_load_dwordx4 v[24:27], v[136:137], off nt
	global_load_dwordx4 v[40:43], v[138:139], off nt
	global_load_dwordx4 v[44:47], v[140:141], off nt
	global_load_dwordx4 v[48:51], v[142:143], off nt
	global_load_dwordx4 v[52:55], v[144:145], off nt
	global_load_dwordx4 v[56:59], v[146:147], off nt
	global_load_dwordx4 v[60:63], v[148:149], off nt
	global_load_dwordx4 v[64:67], v[150:151], off nt
	s_add_u32 s16, s16, 0x90000
	s_addc_u32 s17, s17, 0
.Lmods_pipe:
	v_lshl_add_u64 v[136:137], v[18:19], 0, s[16:17]
	v_add_co_u32_e32 v138, vcc, s18, v136
	s_nop 1
	v_addc_co_u32_e32 v139, vcc, 0, v137, vcc
	v_add_co_u32_e32 v140, vcc, s19, v136
	s_nop 1
	v_addc_co_u32_e32 v141, vcc, 0, v137, vcc
	v_add_co_u32_e32 v142, vcc, s20, v136
	s_nop 1
	v_addc_co_u32_e32 v143, vcc, 0, v137, vcc
	v_add_co_u32_e32 v144, vcc, s21, v136
	s_nop 1
	v_addc_co_u32_e32 v145, vcc, 0, v137, vcc
	v_add_co_u32_e32 v146, vcc, s22, v136
	s_nop 1
	v_addc_co_u32_e32 v147, vcc, 0, v137, vcc
	v_add_co_u32_e32 v148, vcc, s23, v136
	s_nop 1
	v_addc_co_u32_e32 v149, vcc, 0, v137, vcc
	v_add_co_u32_e32 v150, vcc, s24, v136
	s_nop 1
	v_addc_co_u32_e32 v151, vcc, 0, v137, vcc
	global_load_dwordx4 v[104:107], v[136:137], off nt
	global_load_dwordx4 v[108:111], v[138:139], off nt
	global_load_dwordx4 v[112:115], v[140:141], off nt
	global_load_dwordx4 v[116:119], v[142:143], off nt
	global_load_dwordx4 v[120:123], v[144:145], off nt
	global_load_dwordx4 v[124:127], v[146:147], off nt
	global_load_dwordx4 v[128:131], v[148:149], off nt
	global_load_dwordx4 v[132:135], v[150:151], off nt
	s_add_u32 s16, s16, 0x90000
	s_addc_u32 s17, s17, 0
	v_mov_b32_e32 v23, s26
	ds_read_b128 v[28:31], v23
	ds_read_b128 v[32:35], v23 offset:16
	ds_read_b128 v[36:39], v23 offset:512
	ds_read_b128 v[68:71], v23 offset:528
	ds_read_b128 v[72:75], v23 offset:1024
	ds_read_b128 v[76:79], v23 offset:1040
	ds_read_b128 v[80:83], v23 offset:1536
	ds_read_b128 v[84:87], v23 offset:1552
	s_add_i32 s26, s26, 32
	s_waitcnt lgkmcnt(0)
	v_mov_b32_e32 v88, v31
	v_mov_b32_e32 v90, v39
	v_mov_b32_e32 v92, v75
	v_mov_b32_e32 v94, v83
	v_mov_b32_e32 v96, v35
	v_mov_b32_e32 v98, v71
	v_mov_b32_e32 v100, v79
	v_mov_b32_e32 v102, v87
	s_waitcnt vmcnt(15)
	v_pk_fma_f32 v[0:1], v[26:27], v[28:29], v[0:1] op_sel_hi:[1,0,1]
	v_pk_fma_f32 v[6:7], v[24:25], v[28:29], v[6:7] op_sel_hi:[1,0,1]
	v_pk_fma_f32 v[2:3], v[26:27], v[36:37], v[2:3] op_sel_hi:[1,0,1]
	v_pk_fma_f32 v[8:9], v[24:25], v[36:37], v[8:9] op_sel_hi:[1,0,1]
	v_pk_fma_f32 v[10:11], v[26:27], v[72:73], v[10:11] op_sel_hi:[1,0,1]
	v_pk_fma_f32 v[14:15], v[24:25], v[72:73], v[14:15] op_sel_hi:[1,0,1]
	v_pk_fma_f32 v[4:5], v[26:27], v[80:81], v[4:5] op_sel_hi:[1,0,1]
	v_pk_fma_f32 v[12:13], v[24:25], v[80:81], v[12:13] op_sel_hi:[1,0,1]
	s_waitcnt vmcnt(14)
	v_pk_fma_f32 v[6:7], v[40:41], v[28:29], v[6:7] op_sel:[0,1,0]
	v_pk_fma_f32 v[0:1], v[42:43], v[28:29], v[0:1] op_sel:[0,1,0]
	v_pk_fma_f32 v[8:9], v[40:41], v[36:37], v[8:9] op_sel:[0,1,0]
	v_pk_fma_f32 v[2:3], v[42:43], v[36:37], v[2:3] op_sel:[0,1,0]
	v_pk_fma_f32 v[14:15], v[40:41], v[72:73], v[14:15] op_sel:[0,1,0]
	v_pk_fma_f32 v[10:11], v[42:43], v[72:73], v[10:11] op_sel:[0,1,0]
	v_pk_fma_f32 v[12:13], v[40:41], v[80:81], v[12:13] op_sel:[0,1,0]
	v_pk_fma_f32 v[4:5], v[42:43], v[80:81], v[4:5] op_sel:[0,1,0]
	s_waitcnt vmcnt(13)
	v_pk_fma_f32 v[0:1], v[46:47], v[30:31], v[0:1] op_sel_hi:[1,0,1]
	v_pk_fma_f32 v[6:7], v[44:45], v[30:31], v[6:7] op_sel_hi:[1,0,1]
	v_pk_fma_f32 v[2:3], v[46:47], v[38:39], v[2:3] op_sel_hi:[1,0,1]
	v_pk_fma_f32 v[8:9], v[44:45], v[38:39], v[8:9] op_sel_hi:[1,0,1]
	v_pk_fma_f32 v[10:11], v[46:47], v[74:75], v[10:11] op_sel_hi:[1,0,1]
	v_pk_fma_f32 v[14:15], v[44:45], v[74:75], v[14:15] op_sel_hi:[1,0,1]
	v_pk_fma_f32 v[4:5], v[46:47], v[82:83], v[4:5] op_sel_hi:[1,0,1]
	v_pk_fma_f32 v[12:13], v[44:45], v[82:83], v[12:13] op_sel_hi:[1,0,1]
	s_waitcnt vmcnt(12)
	v_pk_fma_f32 v[0:1], v[50:51], v[88:89], v[0:1] op_sel_hi:[1,0,1]
	v_pk_fma_f32 v[6:7], v[48:49], v[88:89], v[6:7] op_sel_hi:[1,0,1]
	v_pk_fma_f32 v[2:3], v[50:51], v[90:91], v[2:3] op_sel_hi:[1,0,1]
	v_pk_fma_f32 v[8:9], v[48:49], v[90:91], v[8:9] op_sel_hi:[1,0,1]
	v_pk_fma_f32 v[10:11], v[50:51], v[92:93], v[10:11] op_sel_hi:[1,0,1]
	v_pk_fma_f32 v[14:15], v[48:49], v[92:93], v[14:15] op_sel_hi:[1,0,1]
	v_pk_fma_f32 v[4:5], v[50:51], v[94:95], v[4:5] op_sel_hi:[1,0,1]
	v_pk_fma_f32 v[12:13], v[48:49], v[94:95], v[12:13] op_sel_hi:[1,0,1]
	s_waitcnt vmcnt(11)
	v_pk_fma_f32 v[0:1], v[54:55], v[32:33], v[0:1] op_sel_hi:[1,0,1]
	v_pk_fma_f32 v[6:7], v[52:53], v[32:33], v[6:7] op_sel_hi:[1,0,1]
	v_pk_fma_f32 v[2:3], v[54:55], v[68:69], v[2:3] op_sel_hi:[1,0,1]
	v_pk_fma_f32 v[8:9], v[52:53], v[68:69], v[8:9] op_sel_hi:[1,0,1]
	v_pk_fma_f32 v[10:11], v[54:55], v[76:77], v[10:11] op_sel_hi:[1,0,1]
	v_pk_fma_f32 v[14:15], v[52:53], v[76:77], v[14:15] op_sel_hi:[1,0,1]
	v_pk_fma_f32 v[4:5], v[54:55], v[84:85], v[4:5] op_sel_hi:[1,0,1]
	v_pk_fma_f32 v[12:13], v[52:53], v[84:85], v[12:13] op_sel_hi:[1,0,1]
	s_waitcnt vmcnt(10)
; __device__ __forceinline__ void mods_item(CArgs a, float* mods, LAS float* scr, int item, int lane) {
;     ...
; #pragma unroll 8
;     for (int kk = 0; kk < 128; ++kk) {
;         const f32x4 w = __builtin_nontemporal_load((const f32x4*)(wp + (size_t)kk * (NMOD * D)));
;         s0 += w * scr[kk]; s1 += w * scr[128 + kk]; s2 += w * scr[256 + kk]; s3 += w * scr[384 + kk];
;     }
	v_pk_fma_f32 v[0:1], v[58:59], v[32:33], v[0:1] op_sel:[0,1,0]
	v_pk_fma_f32 v[6:7], v[56:57], v[32:33], v[6:7] op_sel:[0,1,0]
	v_pk_fma_f32 v[2:3], v[58:59], v[68:69], v[2:3] op_sel:[0,1,0]
	v_pk_fma_f32 v[8:9], v[56:57], v[68:69], v[8:9] op_sel:[0,1,0]
	v_pk_fma_f32 v[10:11], v[58:59], v[76:77], v[10:11] op_sel:[0,1,0]
	v_pk_fma_f32 v[14:15], v[56:57], v[76:77], v[14:15] op_sel:[0,1,0]
	v_pk_fma_f32 v[4:5], v[58:59], v[84:85], v[4:5] op_sel:[0,1,0]
	v_pk_fma_f32 v[12:13], v[56:57], v[84:85], v[12:13] op_sel:[0,1,0]
	s_waitcnt vmcnt(9)
	v_pk_fma_f32 v[0:1], v[62:63], v[34:35], v[0:1] op_sel_hi:[1,0,1]
	v_pk_fma_f32 v[6:7], v[60:61], v[34:35], v[6:7] op_sel_hi:[1,0,1]
	v_pk_fma_f32 v[2:3], v[62:63], v[70:71], v[2:3] op_sel_hi:[1,0,1]
	v_pk_fma_f32 v[8:9], v[60:61], v[70:71], v[8:9] op_sel_hi:[1,0,1]
	v_pk_fma_f32 v[10:11], v[62:63], v[78:79], v[10:11] op_sel_hi:[1,0,1]
	v_pk_fma_f32 v[14:15], v[60:61], v[78:79], v[14:15] op_sel_hi:[1,0,1]
	v_pk_fma_f32 v[4:5], v[62:63], v[86:87], v[4:5] op_sel_hi:[1,0,1]
	v_pk_fma_f32 v[12:13], v[60:61], v[86:87], v[12:13] op_sel_hi:[1,0,1]
	s_waitcnt vmcnt(8)
	v_pk_fma_f32 v[0:1], v[66:67], v[96:97], v[0:1] op_sel_hi:[1,0,1]
	v_pk_fma_f32 v[6:7], v[64:65], v[96:97], v[6:7] op_sel_hi:[1,0,1]
	v_pk_fma_f32 v[2:3], v[66:67], v[98:99], v[2:3] op_sel_hi:[1,0,1]
	v_pk_fma_f32 v[8:9], v[64:65], v[98:99], v[8:9] op_sel_hi:[1,0,1]
	v_pk_fma_f32 v[10:11], v[66:67], v[100:101], v[10:11] op_sel_hi:[1,0,1]
	v_pk_fma_f32 v[14:15], v[64:65], v[100:101], v[14:15] op_sel_hi:[1,0,1]
	v_pk_fma_f32 v[4:5], v[66:67], v[102:103], v[4:5] op_sel_hi:[1,0,1]
	v_pk_fma_f32 v[12:13], v[64:65], v[102:103], v[12:13] op_sel_hi:[1,0,1]
	s_cmp_eq_u32 s16, 0x900000
	s_cbranch_scc1 .Lmods_tail
	v_lshl_add_u64 v[136:137], v[18:19], 0, s[16:17]
	v_add_co_u32_e32 v138, vcc, s18, v136
	s_nop 1
	v_addc_co_u32_e32 v139, vcc, 0, v137, vcc
	v_add_co_u32_e32 v140, vcc, s19, v136
	s_nop 1
	v_addc_co_u32_e32 v141, vcc, 0, v137, vcc
	v_add_co_u32_e32 v142, vcc, s20, v136
	s_nop 1
	v_addc_co_u32_e32 v143, vcc, 0, v137, vcc
	v_add_co_u32_e32 v144, vcc, s21, v136
	s_nop 1
	v_addc_co_u32_e32 v145, vcc, 0, v137, vcc
	v_add_co_u32_e32 v146, vcc, s22, v136
	s_nop 1
	v_addc_co_u32_e32 v147, vcc, 0, v137, vcc
	v_add_co_u32_e32 v148, vcc, s23, v136
	s_nop 1
	v_addc_co_u32_e32 v149, vcc, 0, v137, vcc
	v_add_co_u32_e32 v150, vcc, s24, v136
	s_nop 1
	v_addc_co_u32_e32 v151, vcc, 0, v137, vcc
	global_load_dwordx4 v[24:27], v[136:137], off nt
	global_load_dwordx4 v[40:43], v[138:139], off nt
	global_load_dwordx4 v[44:47], v[140:141], off nt
	global_load_dwordx4 v[48:51], v[142:143], off nt
	global_load_dwordx4 v[52:55], v[144:145], off nt
	global_load_dwordx4 v[56:59], v[146:147], off nt
	global_load_dwordx4 v[60:63], v[148:149], off nt
	global_load_dwordx4 v[64:67], v[150:151], off nt
	s_add_u32 s16, s16, 0x90000
	s_addc_u32 s17, s17, 0
	v_mov_b32_e32 v23, s26
	ds_read_b128 v[28:31], v23
	ds_read_b128 v[32:35], v23 offset:16
	ds_read_b128 v[36:39], v23 offset:512
	ds_read_b128 v[68:71], v23 offset:528
	ds_read_b128 v[72:75], v23 offset:1024
	ds_read_b128 v[76:79], v23 offset:1040
	ds_read_b128 v[80:83], v23 offset:1536
	ds_read_b128 v[84:87], v23 offset:1552
	s_add_i32 s26, s26, 32
	s_waitcnt lgkmcnt(0)
	v_mov_b32_e32 v88, v31
	v_mov_b32_e32 v90, v39
	v_mov_b32_e32 v92, v75
	v_mov_b32_e32 v94, v83
	v_mov_b32_e32 v96, v35
	v_mov_b32_e32 v98, v71
	v_mov_b32_e32 v100, v79
	v_mov_b32_e32 v102, v87
	s_waitcnt vmcnt(15)
	v_pk_fma_f32 v[0:1], v[106:107], v[28:29], v[0:1] op_sel_hi:[1,0,1]
	v_pk_fma_f32 v[6:7], v[104:105], v[28:29], v[6:7] op_sel_hi:[1,0,1]
	v_pk_fma_f32 v[2:3], v[106:107], v[36:37], v[2:3] op_sel_hi:[1,0,1]
	v_pk_fma_f32 v[8:9], v[104:105], v[36:37], v[8:9] op_sel_hi:[1,0,1]
	v_pk_fma_f32 v[10:11], v[106:107], v[72:73], v[10:11] op_sel_hi:[1,0,1]
	v_pk_fma_f32 v[14:15], v[104:105], v[72:73], v[14:15] op_sel_hi:[1,0,1]
	v_pk_fma_f32 v[4:5], v[106:107], v[80:81], v[4:5] op_sel_hi:[1,0,1]
	v_pk_fma_f32 v[12:13], v[104:105], v[80:81], v[12:13] op_sel_hi:[1,0,1]
	s_waitcnt vmcnt(14)
	v_pk_fma_f32 v[6:7], v[108:109], v[28:29], v[6:7] op_sel:[0,1,0]
	v_pk_fma_f32 v[0:1], v[110:111], v[28:29], v[0:1] op_sel:[0,1,0]
	v_pk_fma_f32 v[8:9], v[108:109], v[36:37], v[8:9] op_sel:[0,1,0]
	v_pk_fma_f32 v[2:3], v[110:111], v[36:37], v[2:3] op_sel:[0,1,0]
	v_pk_fma_f32 v[14:15], v[108:109], v[72:73], v[14:15] op_sel:[0,1,0]
	v_pk_fma_f32 v[10:11], v[110:111], v[72:73], v[10:11] op_sel:[0,1,0]
	v_pk_fma_f32 v[12:13], v[108:109], v[80:81], v[12:13] op_sel:[0,1,0]
	v_pk_fma_f32 v[4:5], v[110:111], v[80:81], v[4:5] op_sel:[0,1,0]
	s_waitcnt vmcnt(13)
	v_pk_fma_f32 v[0:1], v[114:115], v[30:31], v[0:1] op_sel_hi:[1,0,1]
	v_pk_fma_f32 v[6:7], v[112:113], v[30:31], v[6:7] op_sel_hi:[1,0,1]
	v_pk_fma_f32 v[2:3], v[114:115], v[38:39], v[2:3] op_sel_hi:[1,0,1]
	v_pk_fma_f32 v[8:9], v[112:113], v[38:39], v[8:9] op_sel_hi:[1,0,1]
	v_pk_fma_f32 v[10:11], v[114:115], v[74:75], v[10:11] op_sel_hi:[1,0,1]
	v_pk_fma_f32 v[14:15], v[112:113], v[74:75], v[14:15] op_sel_hi:[1,0,1]
	v_pk_fma_f32 v[4:5], v[114:115], v[82:83], v[4:5] op_sel_hi:[1,0,1]
	v_pk_fma_f32 v[12:13], v[112:113], v[82:83], v[12:13] op_sel_hi:[1,0,1]
	s_waitcnt vmcnt(12)
	v_pk_fma_f32 v[0:1], v[118:119], v[88:89], v[0:1] op_sel_hi:[1,0,1]
	v_pk_fma_f32 v[6:7], v[116:117], v[88:89], v[6:7] op_sel_hi:[1,0,1]
	v_pk_fma_f32 v[2:3], v[118:119], v[90:91], v[2:3] op_sel_hi:[1,0,1]
	v_pk_fma_f32 v[8:9], v[116:117], v[90:91], v[8:9] op_sel_hi:[1,0,1]
	v_pk_fma_f32 v[10:11], v[118:119], v[92:93], v[10:11] op_sel_hi:[1,0,1]
	v_pk_fma_f32 v[14:15], v[116:117], v[92:93], v[14:15] op_sel_hi:[1,0,1]
	v_pk_fma_f32 v[4:5], v[118:119], v[94:95], v[4:5] op_sel_hi:[1,0,1]
	v_pk_fma_f32 v[12:13], v[116:117], v[94:95], v[12:13] op_sel_hi:[1,0,1]
	s_waitcnt vmcnt(11)
; __device__ __forceinline__ void mods_item(CArgs a, float* mods, LAS float* scr, int item, int lane) {
;     ...
; #pragma unroll 8
;     for (int kk = 0; kk < 128; ++kk) {
;         const f32x4 w = __builtin_nontemporal_load((const f32x4*)(wp + (size_t)kk * (NMOD * D)));
;         s0 += w * scr[kk]; s1 += w * scr[128 + kk]; s2 += w * scr[256 + kk]; s3 += w * scr[384 + kk];
;     }
	v_pk_fma_f32 v[0:1], v[122:123], v[32:33], v[0:1] op_sel_hi:[1,0,1]
	v_pk_fma_f32 v[6:7], v[120:121], v[32:33], v[6:7] op_sel_hi:[1,0,1]
	v_pk_fma_f32 v[2:3], v[122:123], v[68:69], v[2:3] op_sel_hi:[1,0,1]
	v_pk_fma_f32 v[8:9], v[120:121], v[68:69], v[8:9] op_sel_hi:[1,0,1]
	v_pk_fma_f32 v[10:11], v[122:123], v[76:77], v[10:11] op_sel_hi:[1,0,1]
	v_pk_fma_f32 v[14:15], v[120:121], v[76:77], v[14:15] op_sel_hi:[1,0,1]
	v_pk_fma_f32 v[4:5], v[122:123], v[84:85], v[4:5] op_sel_hi:[1,0,1]
	v_pk_fma_f32 v[12:13], v[120:121], v[84:85], v[12:13] op_sel_hi:[1,0,1]
	s_waitcnt vmcnt(10)
	v_pk_fma_f32 v[0:1], v[126:127], v[32:33], v[0:1] op_sel:[0,1,0]
	v_pk_fma_f32 v[6:7], v[124:125], v[32:33], v[6:7] op_sel:[0,1,0]
	v_pk_fma_f32 v[2:3], v[126:127], v[68:69], v[2:3] op_sel:[0,1,0]
	v_pk_fma_f32 v[8:9], v[124:125], v[68:69], v[8:9] op_sel:[0,1,0]
	v_pk_fma_f32 v[10:11], v[126:127], v[76:77], v[10:11] op_sel:[0,1,0]
	v_pk_fma_f32 v[14:15], v[124:125], v[76:77], v[14:15] op_sel:[0,1,0]
	v_pk_fma_f32 v[4:5], v[126:127], v[84:85], v[4:5] op_sel:[0,1,0]
	v_pk_fma_f32 v[12:13], v[124:125], v[84:85], v[12:13] op_sel:[0,1,0]
	s_waitcnt vmcnt(9)
	v_pk_fma_f32 v[0:1], v[130:131], v[34:35], v[0:1] op_sel_hi:[1,0,1]
	v_pk_fma_f32 v[6:7], v[128:129], v[34:35], v[6:7] op_sel_hi:[1,0,1]
	v_pk_fma_f32 v[2:3], v[130:131], v[70:71], v[2:3] op_sel_hi:[1,0,1]
	v_pk_fma_f32 v[8:9], v[128:129], v[70:71], v[8:9] op_sel_hi:[1,0,1]
	v_pk_fma_f32 v[10:11], v[130:131], v[78:79], v[10:11] op_sel_hi:[1,0,1]
	v_pk_fma_f32 v[14:15], v[128:129], v[78:79], v[14:15] op_sel_hi:[1,0,1]
	v_pk_fma_f32 v[4:5], v[130:131], v[86:87], v[4:5] op_sel_hi:[1,0,1]
	v_pk_fma_f32 v[12:13], v[128:129], v[86:87], v[12:13] op_sel_hi:[1,0,1]
	s_waitcnt vmcnt(8)
	v_pk_fma_f32 v[0:1], v[134:135], v[96:97], v[0:1] op_sel_hi:[1,0,1]
	v_pk_fma_f32 v[6:7], v[132:133], v[96:97], v[6:7] op_sel_hi:[1,0,1]
	v_pk_fma_f32 v[2:3], v[134:135], v[98:99], v[2:3] op_sel_hi:[1,0,1]
	v_pk_fma_f32 v[8:9], v[132:133], v[98:99], v[8:9] op_sel_hi:[1,0,1]
	v_pk_fma_f32 v[10:11], v[134:135], v[100:101], v[10:11] op_sel_hi:[1,0,1]
	v_pk_fma_f32 v[14:15], v[132:133], v[100:101], v[14:15] op_sel_hi:[1,0,1]
	v_pk_fma_f32 v[4:5], v[134:135], v[102:103], v[4:5] op_sel_hi:[1,0,1]
	v_pk_fma_f32 v[12:13], v[132:133], v[102:103], v[12:13] op_sel_hi:[1,0,1]
	s_branch .Lmods_pipe
; __device__ __forceinline__ void mods_item(CArgs a, float* mods, LAS float* scr, int item, int lane) {
;     ...
; #pragma unroll 8
;     for (int kk = 0; kk < 128; ++kk) {
;         const f32x4 w = __builtin_nontemporal_load((const f32x4*)(wp + (size_t)kk * (NMOD * D)));
;         s0 += w * scr[kk]; s1 += w * scr[128 + kk]; s2 += w * scr[256 + kk]; s3 += w * scr[384 + kk];
;     }
;     if (kc == 0) { const f32x4 bb = *(const f32x4*)(a->b_ada + col); s0 += bb; s1 += bb; s2 += bb; s3 += bb; }
.Lmods_tail:
	v_mov_b32_e32 v23, s26
	ds_read_b128 v[28:31], v23
	ds_read_b128 v[32:35], v23 offset:16
	ds_read_b128 v[36:39], v23 offset:512
	ds_read_b128 v[68:71], v23 offset:528
	ds_read_b128 v[72:75], v23 offset:1024
	ds_read_b128 v[76:79], v23 offset:1040
	ds_read_b128 v[80:83], v23 offset:1536
	ds_read_b128 v[84:87], v23 offset:1552
	s_add_i32 s26, s26, 32
	s_waitcnt lgkmcnt(0)
	v_mov_b32_e32 v88, v31
	v_mov_b32_e32 v90, v39
	v_mov_b32_e32 v92, v75
	v_mov_b32_e32 v94, v83
	v_mov_b32_e32 v96, v35
	v_mov_b32_e32 v98, v71
	v_mov_b32_e32 v100, v79
	v_mov_b32_e32 v102, v87
	s_waitcnt vmcnt(7)
	v_pk_fma_f32 v[0:1], v[106:107], v[28:29], v[0:1] op_sel_hi:[1,0,1]
	v_pk_fma_f32 v[6:7], v[104:105], v[28:29], v[6:7] op_sel_hi:[1,0,1]
	v_pk_fma_f32 v[2:3], v[106:107], v[36:37], v[2:3] op_sel_hi:[1,0,1]
	v_pk_fma_f32 v[8:9], v[104:105], v[36:37], v[8:9] op_sel_hi:[1,0,1]
	v_pk_fma_f32 v[10:11], v[106:107], v[72:73], v[10:11] op_sel_hi:[1,0,1]
	v_pk_fma_f32 v[14:15], v[104:105], v[72:73], v[14:15] op_sel_hi:[1,0,1]
	v_pk_fma_f32 v[4:5], v[106:107], v[80:81], v[4:5] op_sel_hi:[1,0,1]
	v_pk_fma_f32 v[12:13], v[104:105], v[80:81], v[12:13] op_sel_hi:[1,0,1]
	s_waitcnt vmcnt(6)
	v_pk_fma_f32 v[6:7], v[108:109], v[28:29], v[6:7] op_sel:[0,1,0]
	v_pk_fma_f32 v[0:1], v[110:111], v[28:29], v[0:1] op_sel:[0,1,0]
	v_pk_fma_f32 v[8:9], v[108:109], v[36:37], v[8:9] op_sel:[0,1,0]
	v_pk_fma_f32 v[2:3], v[110:111], v[36:37], v[2:3] op_sel:[0,1,0]
	v_pk_fma_f32 v[14:15], v[108:109], v[72:73], v[14:15] op_sel:[0,1,0]
	v_pk_fma_f32 v[10:11], v[110:111], v[72:73], v[10:11] op_sel:[0,1,0]
	v_pk_fma_f32 v[12:13], v[108:109], v[80:81], v[12:13] op_sel:[0,1,0]
	v_pk_fma_f32 v[4:5], v[110:111], v[80:81], v[4:5] op_sel:[0,1,0]
	s_waitcnt vmcnt(5)
	v_pk_fma_f32 v[0:1], v[114:115], v[30:31], v[0:1] op_sel_hi:[1,0,1]
	v_pk_fma_f32 v[6:7], v[112:113], v[30:31], v[6:7] op_sel_hi:[1,0,1]
	v_pk_fma_f32 v[2:3], v[114:115], v[38:39], v[2:3] op_sel_hi:[1,0,1]
	v_pk_fma_f32 v[8:9], v[112:113], v[38:39], v[8:9] op_sel_hi:[1,0,1]
	v_pk_fma_f32 v[10:11], v[114:115], v[74:75], v[10:11] op_sel_hi:[1,0,1]
	v_pk_fma_f32 v[14:15], v[112:113], v[74:75], v[14:15] op_sel_hi:[1,0,1]
	v_pk_fma_f32 v[4:5], v[114:115], v[82:83], v[4:5] op_sel_hi:[1,0,1]
	v_pk_fma_f32 v[12:13], v[112:113], v[82:83], v[12:13] op_sel_hi:[1,0,1]
	s_waitcnt vmcnt(4)
	v_pk_fma_f32 v[0:1], v[118:119], v[88:89], v[0:1] op_sel_hi:[1,0,1]
	v_pk_fma_f32 v[6:7], v[116:117], v[88:89], v[6:7] op_sel_hi:[1,0,1]
	v_pk_fma_f32 v[2:3], v[118:119], v[90:91], v[2:3] op_sel_hi:[1,0,1]
	v_pk_fma_f32 v[8:9], v[116:117], v[90:91], v[8:9] op_sel_hi:[1,0,1]
	v_pk_fma_f32 v[10:11], v[118:119], v[92:93], v[10:11] op_sel_hi:[1,0,1]
	v_pk_fma_f32 v[14:15], v[116:117], v[92:93], v[14:15] op_sel_hi:[1,0,1]
	v_pk_fma_f32 v[4:5], v[118:119], v[94:95], v[4:5] op_sel_hi:[1,0,1]
	v_pk_fma_f32 v[12:13], v[116:117], v[94:95], v[12:13] op_sel_hi:[1,0,1]
	s_waitcnt vmcnt(3)
	v_pk_fma_f32 v[0:1], v[122:123], v[32:33], v[0:1] op_sel_hi:[1,0,1]
	v_pk_fma_f32 v[6:7], v[120:121], v[32:33], v[6:7] op_sel_hi:[1,0,1]
	v_pk_fma_f32 v[2:3], v[122:123], v[68:69], v[2:3] op_sel_hi:[1,0,1]
	v_pk_fma_f32 v[8:9], v[120:121], v[68:69], v[8:9] op_sel_hi:[1,0,1]
	v_pk_fma_f32 v[10:11], v[122:123], v[76:77], v[10:11] op_sel_hi:[1,0,1]
	v_pk_fma_f32 v[14:15], v[120:121], v[76:77], v[14:15] op_sel_hi:[1,0,1]
	v_pk_fma_f32 v[4:5], v[122:123], v[84:85], v[4:5] op_sel_hi:[1,0,1]
	v_pk_fma_f32 v[12:13], v[120:121], v[84:85], v[12:13] op_sel_hi:[1,0,1]
	s_waitcnt vmcnt(2)
	v_pk_fma_f32 v[0:1], v[126:127], v[32:33], v[0:1] op_sel:[0,1,0]
	v_pk_fma_f32 v[6:7], v[124:125], v[32:33], v[6:7] op_sel:[0,1,0]
	v_pk_fma_f32 v[2:3], v[126:127], v[68:69], v[2:3] op_sel:[0,1,0]
	v_pk_fma_f32 v[8:9], v[124:125], v[68:69], v[8:9] op_sel:[0,1,0]
	v_pk_fma_f32 v[10:11], v[126:127], v[76:77], v[10:11] op_sel:[0,1,0]
	v_pk_fma_f32 v[14:15], v[124:125], v[76:77], v[14:15] op_sel:[0,1,0]
	v_pk_fma_f32 v[4:5], v[126:127], v[84:85], v[4:5] op_sel:[0,1,0]
	v_pk_fma_f32 v[12:13], v[124:125], v[84:85], v[12:13] op_sel:[0,1,0]
	s_waitcnt vmcnt(1)
	v_pk_fma_f32 v[0:1], v[130:131], v[34:35], v[0:1] op_sel_hi:[1,0,1]
	v_pk_fma_f32 v[6:7], v[128:129], v[34:35], v[6:7] op_sel_hi:[1,0,1]
	v_pk_fma_f32 v[2:3], v[130:131], v[70:71], v[2:3] op_sel_hi:[1,0,1]
	v_pk_fma_f32 v[8:9], v[128:129], v[70:71], v[8:9] op_sel_hi:[1,0,1]
	v_pk_fma_f32 v[10:11], v[130:131], v[78:79], v[10:11] op_sel_hi:[1,0,1]
	v_pk_fma_f32 v[14:15], v[128:129], v[78:79], v[14:15] op_sel_hi:[1,0,1]
	v_pk_fma_f32 v[4:5], v[130:131], v[86:87], v[4:5] op_sel_hi:[1,0,1]
	v_pk_fma_f32 v[12:13], v[128:129], v[86:87], v[12:13] op_sel_hi:[1,0,1]
	s_waitcnt vmcnt(0)
	v_pk_fma_f32 v[0:1], v[134:135], v[96:97], v[0:1] op_sel_hi:[1,0,1]
	v_pk_fma_f32 v[6:7], v[132:133], v[96:97], v[6:7] op_sel_hi:[1,0,1]
	v_pk_fma_f32 v[2:3], v[134:135], v[98:99], v[2:3] op_sel_hi:[1,0,1]
	v_pk_fma_f32 v[8:9], v[132:133], v[98:99], v[8:9] op_sel_hi:[1,0,1]
	v_pk_fma_f32 v[10:11], v[134:135], v[100:101], v[10:11] op_sel_hi:[1,0,1]
	v_pk_fma_f32 v[14:15], v[132:133], v[100:101], v[14:15] op_sel_hi:[1,0,1]
	v_pk_fma_f32 v[4:5], v[134:135], v[102:103], v[4:5] op_sel_hi:[1,0,1]
	v_pk_fma_f32 v[12:13], v[132:133], v[102:103], v[12:13] op_sel_hi:[1,0,1]
	s_add_i32 s16, s25, 0x47
	s_cmpk_lt_u32 s16, 0x8f
	s_cbranch_scc0 .LBB0_22
	s_load_dwordx2 s[16:17], s[6:7], 0x20
	s_waitcnt lgkmcnt(0)
	v_lshl_add_u64 v[18:19], v[16:17], 2, s[16:17]
	global_load_dwordx4 v[24:27], v[18:19], off
	s_waitcnt vmcnt(0)
	v_pk_add_f32 v[0:1], v[0:1], v[26:27]
	v_pk_add_f32 v[6:7], v[6:7], v[24:25]
	v_pk_add_f32 v[2:3], v[2:3], v[26:27]
	v_pk_add_f32 v[8:9], v[8:9], v[24:25]
	v_pk_add_f32 v[10:11], v[10:11], v[26:27]
	v_pk_add_f32 v[14:15], v[14:15], v[24:25]
	v_pk_add_f32 v[4:5], v[4:5], v[26:27]
	v_pk_add_f32 v[12:13], v[12:13], v[24:25]
	s_branch .LBB0_22
